# adds EpiResid coalesced residual loads/stores via lane transposes, early second-half loads, and batched LDS reads in the sample residual GEMM tail
# speedup vs baseline: 1.0221x; 1.0023x over previous
.LBB0_942:
	v_mov_b32_e32 v133, v199
	v_mov_b32_e32 v134, v198
	s_mov_b32 s31, s44
	s_mov_b32 s40, s61
	s_lshl_b32 s35, s30, 8
	s_lshl_b32 s38, s40, 5
	s_add_i32 s38, s38, s35
	s_ashr_i32 s35, s34, 31
	v_lshl_add_u32 v132, v134, 3, s38
	s_lshl_b64 s[38:39], s[34:35], 19
	s_add_u32 s38, s58, s38
	v_lshl_add_u32 v202, v134, 4, v133
	s_addc_u32 s39, s59, s39
	v_lshl_add_u32 v170, s31, 6, v133
	v_ashrrev_i32_e32 v133, 31, v132
	v_lshl_add_u64 v[168:169], v[132:133], 1, s[38:39]
	v_mbcnt_lo_u32_b32 v243, -1, 0
	v_mbcnt_hi_u32_b32 v243, -1, v243
	v_and_b32_e32 v245, 3, v243
	v_lshrrev_b32_e32 v246, 2, v243
	v_lshlrev_b32_e32 v242, 6, v245
	v_lshl_or_b32 v242, v246, 2, v242
	v_and_b32_e32 v244, 15, v243
	v_lshrrev_b32_e32 v247, 4, v243
	v_lshlrev_b32_e32 v244, 4, v244
	v_lshl_or_b32 v244, v247, 2, v244
	v_sub_u32_e32 v246, v246, v199
	v_sub_u32_e32 v245, v245, v198
	v_lshlrev_b32_e32 v246, 11, v246
	v_lshl_add_u32 v246, v245, 4, v246
	v_ashrrev_i32_e32 v247, 31, v246
	v_lshl_add_u64 v[168:169], v[168:169], 0, v[246:247]
	v_lshlrev_b32_e32 v132, 2, v202
	v_ashrrev_i32_e32 v171, 31, v170
	v_xor_b32_e32 v204, 64, v132
	v_xor_b32_e32 v203, 0x80, v132
	v_lshlrev_b64 v[132:133], 11, v[170:171]
	v_lshl_add_u64 v[196:197], v[168:169], 0, v[132:133]
	global_load_dwordx4 v[206:209], v[196:197], off
	global_load_dwordx4 v[156:159], v[196:197], off offset:256
	v_add_u32_e32 v180, 16, v170
	v_ashrrev_i32_e32 v181, 31, v180
	v_add_u32_e32 v176, 32, v170
	v_lshlrev_b64 v[132:133], 11, v[180:181]
	v_ashrrev_i32_e32 v177, 31, v176
	v_add_u32_e32 v172, 48, v170
	v_lshl_add_u64 v[182:183], v[168:169], 0, v[132:133]
	v_lshlrev_b64 v[132:133], 11, v[176:177]
	v_ashrrev_i32_e32 v173, 31, v172
	v_lshl_add_u64 v[178:179], v[168:169], 0, v[132:133]
	v_lshlrev_b64 v[132:133], 11, v[172:173]
	v_lshl_add_u64 v[174:175], v[168:169], 0, v[132:133]
	v_cmp_eq_u32_e32 vcc, 0, v134
	global_load_dwordx4 v[152:155], v[182:183], off
	global_load_dwordx4 v[148:151], v[182:183], off offset:256
	global_load_dwordx4 v[144:147], v[178:179], off
	global_load_dwordx4 v[136:139], v[178:179], off offset:256
	global_load_dwordx4 v[140:143], v[174:175], off
	global_load_dwordx4 v[132:135], v[174:175], off offset:256
	v_add_u32_e32 v252, 0x80, v170
	v_ashrrev_i32_e32 v253, 31, v252
	v_lshlrev_b64 v[252:253], 11, v[252:253]
	v_lshl_add_u64 v[252:253], v[168:169], 0, v[252:253]
	global_load_dwordx4 v[184:187], v[252:253], off
	global_load_dwordx4 v[192:195], v[252:253], off offset:256
	v_add_u32_e32 v246, 0x90, v170
	v_ashrrev_i32_e32 v247, 31, v246
	v_lshlrev_b64 v[246:247], 11, v[246:247]
	v_lshl_add_u64 v[246:247], v[168:169], 0, v[246:247]
	global_load_dwordx4 v[210:213], v[246:247], off
	global_load_dwordx4 v[214:217], v[246:247], off offset:256
	v_add_u32_e32 v252, 0xa0, v170
	v_ashrrev_i32_e32 v253, 31, v252
	v_lshlrev_b64 v[252:253], 11, v[252:253]
	v_lshl_add_u64 v[252:253], v[168:169], 0, v[252:253]
	global_load_dwordx4 v[218:221], v[252:253], off
	global_load_dwordx4 v[222:225], v[252:253], off offset:256
	v_add_u32_e32 v246, 0xb0, v170
	v_ashrrev_i32_e32 v247, 31, v246
	v_lshlrev_b64 v[246:247], 11, v[246:247]
	v_lshl_add_u64 v[246:247], v[168:169], 0, v[246:247]
	global_load_dwordx4 v[234:237], v[246:247], off
	global_load_dwordx4 v[248:251], v[246:247], off offset:256
	s_lshl_b32 s35, s40, 2
	s_add_i32 s35, s35, 0
	s_add_i32 s35, s35, 0x20000
	s_waitcnt vmcnt(15)
	ds_bpermute_b32 v206, v244, v206
	ds_bpermute_b32 v207, v244, v207
	ds_bpermute_b32 v208, v244, v208
	ds_bpermute_b32 v209, v244, v209
	s_waitcnt vmcnt(14)
	ds_bpermute_b32 v156, v244, v156
	ds_bpermute_b32 v157, v244, v157
	ds_bpermute_b32 v158, v244, v158
	ds_bpermute_b32 v159, v244, v159
	s_waitcnt vmcnt(13)
	ds_bpermute_b32 v152, v244, v152
	ds_bpermute_b32 v153, v244, v153
	ds_bpermute_b32 v154, v244, v154
	ds_bpermute_b32 v155, v244, v155
	s_waitcnt vmcnt(12)
	ds_bpermute_b32 v148, v244, v148
	ds_bpermute_b32 v149, v244, v149
	ds_bpermute_b32 v150, v244, v150
	ds_bpermute_b32 v151, v244, v151
	s_waitcnt vmcnt(11)
	ds_bpermute_b32 v144, v244, v144
	ds_bpermute_b32 v145, v244, v145
	ds_bpermute_b32 v146, v244, v146
	ds_bpermute_b32 v147, v244, v147
	s_waitcnt vmcnt(10)
	ds_bpermute_b32 v136, v244, v136
	ds_bpermute_b32 v137, v244, v137
	ds_bpermute_b32 v138, v244, v138
	ds_bpermute_b32 v139, v244, v139
	s_waitcnt vmcnt(9)
	ds_bpermute_b32 v140, v244, v140
	ds_bpermute_b32 v141, v244, v141
	ds_bpermute_b32 v142, v244, v142
	ds_bpermute_b32 v143, v244, v143
	s_waitcnt vmcnt(8)
	ds_bpermute_b32 v132, v244, v132
	ds_bpermute_b32 v133, v244, v133
	ds_bpermute_b32 v134, v244, v134
	ds_bpermute_b32 v135, v244, v135
	s_waitcnt lgkmcnt(0)
	v_lshlrev_b32_e32 v171, 16, v206
	v_add_f32_e32 v128, v128, v171
	v_and_b32_e32 v171, 0xffff0000, v206
	v_add_f32_e32 v129, v129, v171
	v_lshlrev_b32_e32 v171, 16, v207
	v_add_f32_e32 v130, v130, v171
	v_and_b32_e32 v171, 0xffff0000, v207
	v_add_f32_e32 v131, v131, v171
	v_lshlrev_b32_e32 v171, 16, v208
	v_add_f32_e32 v171, v124, v171
	v_and_b32_e32 v124, 0xffff0000, v208
	v_add_f32_e32 v173, v125, v124
	v_lshlrev_b32_e32 v124, 16, v209
	v_add_f32_e32 v177, v126, v124
	v_and_b32_e32 v124, 0xffff0000, v209
	v_add_f32_e32 v181, v127, v124
	v_cvt_pk_bf16_f32 v124, v128, v129
	v_cvt_pk_bf16_f32 v125, v130, v131
	v_cvt_pk_bf16_f32 v126, v171, v173
	v_cvt_pk_bf16_f32 v127, v177, v181
	ds_bpermute_b32 v226, v242, v124
	ds_bpermute_b32 v227, v242, v125
	ds_bpermute_b32 v228, v242, v126
	ds_bpermute_b32 v229, v242, v127
	s_nop 1
	v_mul_f32_e32 v124, v129, v129
	v_mul_f32_e32 v125, v131, v131
	v_fmac_f32_e32 v124, v128, v128
	v_fmac_f32_e32 v125, v130, v130
	v_add_f32_e32 v124, v124, v125
	v_mul_f32_e32 v125, v173, v173
	v_mul_f32_e32 v126, v181, v181
	v_fmac_f32_e32 v125, v171, v171
	v_fmac_f32_e32 v126, v177, v177
	v_add_f32_e32 v125, v125, v126
	v_add_f32_e32 v124, v124, v125
	v_lshlrev_b32_e32 v125, 16, v156
	v_add_f32_e32 v120, v120, v125
	v_and_b32_e32 v125, 0xffff0000, v156
	v_add_f32_e32 v121, v121, v125
	v_lshlrev_b32_e32 v125, 16, v157
	v_add_f32_e32 v122, v122, v125
	v_and_b32_e32 v125, 0xffff0000, v157
	v_add_f32_e32 v123, v123, v125
	v_lshlrev_b32_e32 v125, 16, v158
	v_add_f32_e32 v125, v116, v125
	v_and_b32_e32 v116, 0xffff0000, v158
	v_add_f32_e32 v126, v117, v116
	v_lshlrev_b32_e32 v116, 16, v159
	v_add_f32_e32 v127, v118, v116
	v_and_b32_e32 v116, 0xffff0000, v159
	v_add_f32_e32 v128, v119, v116
	v_cvt_pk_bf16_f32 v116, v120, v121
	v_cvt_pk_bf16_f32 v117, v122, v123
	v_cvt_pk_bf16_f32 v118, v125, v126
	v_cvt_pk_bf16_f32 v119, v127, v128
	ds_bpermute_b32 v230, v242, v116
	ds_bpermute_b32 v231, v242, v117
	ds_bpermute_b32 v232, v242, v118
	ds_bpermute_b32 v233, v242, v119
	s_waitcnt lgkmcnt(4)
	global_store_dwordx4 v[196:197], v[226:229], off
	s_nop 1
	v_mul_f32_e32 v116, v121, v121
	v_mul_f32_e32 v117, v123, v123
	v_fmac_f32_e32 v116, v120, v120
	v_fmac_f32_e32 v117, v122, v122
	v_add_f32_e32 v116, v116, v117
	v_mul_f32_e32 v117, v126, v126
	v_mul_f32_e32 v118, v128, v128
	v_fmac_f32_e32 v117, v125, v125
	v_fmac_f32_e32 v118, v127, v127
	v_add_f32_e32 v117, v117, v118
	v_add_f32_e32 v116, v116, v117
	v_add_f32_e32 v116, v124, v116
	ds_bpermute_b32 v117, v204, v116
	s_waitcnt lgkmcnt(0)
	v_add_f32_e32 v116, v116, v117
	ds_bpermute_b32 v117, v203, v116
	s_and_saveexec_b64 s[38:39], vcc
	s_cbranch_execz .LBB0_944
	v_lshl_add_u32 v118, v170, 4, s35
	s_waitcnt lgkmcnt(0)
	v_add_f32_e32 v116, v116, v117
	ds_write_b32 v118, v116
.LBB0_944:
	s_or_b64 exec, exec, s[38:39]
	v_lshlrev_b32_e32 v116, 16, v152
	v_add_f32_e32 v112, v112, v116
	v_and_b32_e32 v116, 0xffff0000, v152
	v_add_f32_e32 v113, v113, v116
	v_lshlrev_b32_e32 v116, 16, v153
	v_add_f32_e32 v114, v114, v116
	v_and_b32_e32 v116, 0xffff0000, v153
	v_add_f32_e32 v115, v115, v116
	v_lshlrev_b32_e32 v116, 16, v154
	v_add_f32_e32 v116, v108, v116
	v_and_b32_e32 v108, 0xffff0000, v154
	s_waitcnt lgkmcnt(0)
	v_add_f32_e32 v117, v109, v108
	v_lshlrev_b32_e32 v108, 16, v155
	v_add_f32_e32 v118, v110, v108
	v_and_b32_e32 v108, 0xffff0000, v155
	v_mul_f32_e32 v110, v113, v113
	v_add_f32_e32 v111, v111, v108
	v_cvt_pk_bf16_f32 v108, v112, v113
	v_fmac_f32_e32 v110, v112, v112
	v_mul_f32_e32 v112, v115, v115
	v_fmac_f32_e32 v112, v114, v114
	v_add_f32_e32 v110, v110, v112
	v_mul_f32_e32 v112, v117, v117
	v_mul_f32_e32 v113, v111, v111
	v_fmac_f32_e32 v112, v116, v116
	v_fmac_f32_e32 v113, v118, v118
	v_add_f32_e32 v112, v112, v113
	v_add_f32_e32 v110, v110, v112
	v_lshlrev_b32_e32 v112, 16, v148
	v_add_f32_e32 v104, v104, v112
	v_and_b32_e32 v112, 0xffff0000, v148
	v_add_f32_e32 v105, v105, v112
	v_lshlrev_b32_e32 v112, 16, v149
	v_add_f32_e32 v106, v106, v112
	v_and_b32_e32 v112, 0xffff0000, v149
	v_add_f32_e32 v107, v107, v112
	v_lshlrev_b32_e32 v112, 16, v150
	v_add_f32_e32 v112, v100, v112
	v_and_b32_e32 v100, 0xffff0000, v150
	v_add_f32_e32 v113, v101, v100
	v_lshlrev_b32_e32 v100, 16, v151
	v_cvt_pk_bf16_f32 v109, v114, v115
	v_add_f32_e32 v114, v102, v100
	v_and_b32_e32 v100, 0xffff0000, v151
	v_add_f32_e32 v115, v103, v100
	v_mul_f32_e32 v100, v105, v105
	v_mul_f32_e32 v101, v107, v107
	v_fmac_f32_e32 v100, v104, v104
	v_fmac_f32_e32 v101, v106, v106
	v_add_f32_e32 v100, v100, v101
	v_mul_f32_e32 v101, v113, v113
	v_mul_f32_e32 v102, v115, v115
	v_fmac_f32_e32 v101, v112, v112
	v_fmac_f32_e32 v102, v114, v114
	v_add_f32_e32 v101, v101, v102
	v_add_f32_e32 v100, v100, v101
	v_add_f32_e32 v100, v110, v100
	ds_bpermute_b32 v101, v204, v100
	v_cvt_pk_bf16_f32 v110, v116, v117
	v_cvt_pk_bf16_f32 v111, v118, v111
	ds_bpermute_b32 v226, v242, v108
	ds_bpermute_b32 v227, v242, v109
	ds_bpermute_b32 v228, v242, v110
	ds_bpermute_b32 v229, v242, v111
	s_waitcnt lgkmcnt(4)
	global_store_dwordx4 v[196:197], v[230:233], off offset:256
	v_cvt_pk_bf16_f32 v102, v104, v105
	s_waitcnt lgkmcnt(0)
	v_add_f32_e32 v100, v100, v101
	ds_bpermute_b32 v101, v203, v100
	v_cvt_pk_bf16_f32 v103, v106, v107
	v_cvt_pk_bf16_f32 v104, v112, v113
	v_cvt_pk_bf16_f32 v105, v114, v115
	ds_bpermute_b32 v230, v242, v102
	ds_bpermute_b32 v231, v242, v103
	ds_bpermute_b32 v232, v242, v104
	ds_bpermute_b32 v233, v242, v105
	s_waitcnt lgkmcnt(4)
	global_store_dwordx4 v[182:183], v[226:229], off
	s_and_saveexec_b64 s[38:39], vcc
	s_cbranch_execz .LBB0_946
	v_lshl_add_u32 v102, v180, 4, s35
	s_waitcnt lgkmcnt(0)
	v_add_f32_e32 v100, v100, v101
	ds_write_b32 v102, v100
.LBB0_946:
	s_or_b64 exec, exec, s[38:39]
	v_lshlrev_b32_e32 v100, 16, v144
	v_add_f32_e32 v96, v96, v100
	v_and_b32_e32 v100, 0xffff0000, v144
	v_add_f32_e32 v97, v97, v100
	v_lshlrev_b32_e32 v100, 16, v145
	v_add_f32_e32 v98, v98, v100
	v_and_b32_e32 v100, 0xffff0000, v145
	v_add_f32_e32 v99, v99, v100
	v_lshlrev_b32_e32 v100, 16, v146
	v_add_f32_e32 v100, v92, v100
	v_and_b32_e32 v92, 0xffff0000, v146
	s_waitcnt lgkmcnt(0)
	v_add_f32_e32 v101, v93, v92
	v_lshlrev_b32_e32 v92, 16, v147
	v_add_f32_e32 v102, v94, v92
	v_and_b32_e32 v92, 0xffff0000, v147
	v_mul_f32_e32 v94, v97, v97
	v_add_f32_e32 v95, v95, v92
	v_cvt_pk_bf16_f32 v92, v96, v97
	v_fmac_f32_e32 v94, v96, v96
	v_mul_f32_e32 v96, v99, v99
	v_fmac_f32_e32 v96, v98, v98
	v_add_f32_e32 v94, v94, v96
	v_mul_f32_e32 v96, v101, v101
	v_mul_f32_e32 v97, v95, v95
	v_fmac_f32_e32 v96, v100, v100
	v_fmac_f32_e32 v97, v102, v102
	v_add_f32_e32 v96, v96, v97
	v_add_f32_e32 v94, v94, v96
	v_lshlrev_b32_e32 v96, 16, v136
	v_add_f32_e32 v88, v88, v96
	v_and_b32_e32 v96, 0xffff0000, v136
	v_add_f32_e32 v89, v89, v96
	v_lshlrev_b32_e32 v96, 16, v137
	v_add_f32_e32 v90, v90, v96
	v_and_b32_e32 v96, 0xffff0000, v137
	v_add_f32_e32 v91, v91, v96
	v_lshlrev_b32_e32 v96, 16, v138
	v_add_f32_e32 v96, v84, v96
	v_and_b32_e32 v84, 0xffff0000, v138
	v_add_f32_e32 v97, v85, v84
	v_lshlrev_b32_e32 v84, 16, v139
	v_cvt_pk_bf16_f32 v93, v98, v99
	v_add_f32_e32 v98, v86, v84
	v_and_b32_e32 v84, 0xffff0000, v139
	v_add_f32_e32 v99, v87, v84
	v_mul_f32_e32 v84, v89, v89
	v_mul_f32_e32 v85, v91, v91
	v_fmac_f32_e32 v84, v88, v88
	v_fmac_f32_e32 v85, v90, v90
	v_add_f32_e32 v84, v84, v85
	v_mul_f32_e32 v85, v97, v97
	v_mul_f32_e32 v86, v99, v99
	v_fmac_f32_e32 v85, v96, v96
	v_fmac_f32_e32 v86, v98, v98
	v_add_f32_e32 v85, v85, v86
	v_add_f32_e32 v84, v84, v85
	v_add_f32_e32 v84, v94, v84
	ds_bpermute_b32 v85, v204, v84
	v_cvt_pk_bf16_f32 v94, v100, v101
	v_cvt_pk_bf16_f32 v95, v102, v95
	ds_bpermute_b32 v226, v242, v92
	ds_bpermute_b32 v227, v242, v93
	ds_bpermute_b32 v228, v242, v94
	ds_bpermute_b32 v229, v242, v95
	s_waitcnt lgkmcnt(4)
	global_store_dwordx4 v[182:183], v[230:233], off offset:256
	v_cvt_pk_bf16_f32 v86, v88, v89
	s_waitcnt lgkmcnt(0)
	v_add_f32_e32 v84, v84, v85
	ds_bpermute_b32 v85, v203, v84
	v_cvt_pk_bf16_f32 v87, v90, v91
	v_cvt_pk_bf16_f32 v88, v96, v97
	v_cvt_pk_bf16_f32 v89, v98, v99
	ds_bpermute_b32 v230, v242, v86
	ds_bpermute_b32 v231, v242, v87
	ds_bpermute_b32 v232, v242, v88
	ds_bpermute_b32 v233, v242, v89
	s_waitcnt lgkmcnt(4)
	global_store_dwordx4 v[178:179], v[226:229], off
	s_and_saveexec_b64 s[38:39], vcc
	s_cbranch_execz .LBB0_948
	v_lshl_add_u32 v86, v176, 4, s35
	s_waitcnt lgkmcnt(0)
	v_add_f32_e32 v84, v84, v85
	ds_write_b32 v86, v84
.LBB0_948:
	s_or_b64 exec, exec, s[38:39]
	v_lshlrev_b32_e32 v84, 16, v140
	v_add_f32_e32 v80, v80, v84
	v_and_b32_e32 v84, 0xffff0000, v140
	v_add_f32_e32 v81, v81, v84
	v_lshlrev_b32_e32 v84, 16, v141
	v_add_f32_e32 v82, v82, v84
	v_and_b32_e32 v84, 0xffff0000, v141
	v_add_f32_e32 v83, v83, v84
	v_lshlrev_b32_e32 v84, 16, v142
	v_add_f32_e32 v84, v76, v84
	v_and_b32_e32 v76, 0xffff0000, v142
	s_waitcnt lgkmcnt(0)
	v_add_f32_e32 v85, v77, v76
	v_lshlrev_b32_e32 v76, 16, v143
	v_add_f32_e32 v86, v78, v76
	v_and_b32_e32 v76, 0xffff0000, v143
	v_mul_f32_e32 v78, v81, v81
	v_add_f32_e32 v79, v79, v76
	v_cvt_pk_bf16_f32 v76, v80, v81
	v_fmac_f32_e32 v78, v80, v80
	v_mul_f32_e32 v80, v83, v83
	v_fmac_f32_e32 v80, v82, v82
	v_add_f32_e32 v78, v78, v80
	v_mul_f32_e32 v80, v85, v85
	v_mul_f32_e32 v81, v79, v79
	v_fmac_f32_e32 v80, v84, v84
	v_fmac_f32_e32 v81, v86, v86
	v_add_f32_e32 v80, v80, v81
	v_add_f32_e32 v78, v78, v80
	v_lshlrev_b32_e32 v80, 16, v132
	v_add_f32_e32 v72, v72, v80
	v_and_b32_e32 v80, 0xffff0000, v132
	v_add_f32_e32 v73, v73, v80
	v_lshlrev_b32_e32 v80, 16, v133
	v_add_f32_e32 v74, v74, v80
	v_and_b32_e32 v80, 0xffff0000, v133
	v_add_f32_e32 v75, v75, v80
	v_lshlrev_b32_e32 v80, 16, v134
	v_add_f32_e32 v80, v68, v80
	v_and_b32_e32 v68, 0xffff0000, v134
	v_add_f32_e32 v81, v69, v68
	v_lshlrev_b32_e32 v68, 16, v135
	v_cvt_pk_bf16_f32 v77, v82, v83
	v_add_f32_e32 v82, v70, v68
	v_and_b32_e32 v68, 0xffff0000, v135
	v_add_f32_e32 v83, v71, v68
	v_mul_f32_e32 v68, v73, v73
	v_mul_f32_e32 v69, v75, v75
	v_fmac_f32_e32 v68, v72, v72
	v_fmac_f32_e32 v69, v74, v74
	v_add_f32_e32 v68, v68, v69
	v_mul_f32_e32 v69, v81, v81
	v_mul_f32_e32 v70, v83, v83
	v_fmac_f32_e32 v69, v80, v80
	v_fmac_f32_e32 v70, v82, v82
	v_add_f32_e32 v69, v69, v70
	v_add_f32_e32 v68, v68, v69
	v_add_f32_e32 v68, v78, v68
	ds_bpermute_b32 v69, v204, v68
	v_cvt_pk_bf16_f32 v78, v84, v85
	v_cvt_pk_bf16_f32 v79, v86, v79
	ds_bpermute_b32 v226, v242, v76
	ds_bpermute_b32 v227, v242, v77
	ds_bpermute_b32 v228, v242, v78
	ds_bpermute_b32 v229, v242, v79
	s_waitcnt lgkmcnt(4)
	global_store_dwordx4 v[178:179], v[230:233], off offset:256
	v_cvt_pk_bf16_f32 v70, v72, v73
	s_waitcnt lgkmcnt(0)
	v_add_f32_e32 v68, v68, v69
	ds_bpermute_b32 v69, v203, v68
	v_cvt_pk_bf16_f32 v71, v74, v75
	v_cvt_pk_bf16_f32 v72, v80, v81
	v_cvt_pk_bf16_f32 v73, v82, v83
	ds_bpermute_b32 v230, v242, v70
	ds_bpermute_b32 v231, v242, v71
	ds_bpermute_b32 v232, v242, v72
	ds_bpermute_b32 v233, v242, v73
	s_waitcnt lgkmcnt(4)
	global_store_dwordx4 v[174:175], v[226:229], off
	s_and_saveexec_b64 s[38:39], vcc
	s_cbranch_execz .LBB0_950
	v_lshl_add_u32 v70, v172, 4, s35
	s_waitcnt lgkmcnt(0)
	v_add_f32_e32 v68, v68, v69
	ds_write_b32 v70, v68
.LBB0_950:
	s_or_b64 exec, exec, s[38:39]
	v_add_u32_e32 v108, 0x80, v170
	v_ashrrev_i32_e32 v109, 31, v108
	s_waitcnt lgkmcnt(0)
	v_lshlrev_b64 v[68:69], 11, v[108:109]
	v_lshl_add_u64 v[110:111], v[168:169], 0, v[68:69]
	v_add_u32_e32 v104, 0x90, v170
	v_ashrrev_i32_e32 v105, 31, v104
	v_add_u32_e32 v100, 0xa0, v170
	v_lshlrev_b64 v[68:69], 11, v[104:105]
	v_ashrrev_i32_e32 v101, 31, v100
	v_add_u32_e32 v96, 0xb0, v170
	v_lshl_add_u64 v[106:107], v[168:169], 0, v[68:69]
	v_lshlrev_b64 v[68:69], 11, v[100:101]
	v_ashrrev_i32_e32 v97, 31, v96
	v_lshl_add_u64 v[102:103], v[168:169], 0, v[68:69]
	v_lshlrev_b64 v[68:69], 11, v[96:97]
	v_lshl_add_u64 v[98:99], v[168:169], 0, v[68:69]
	s_waitcnt vmcnt(7)
	ds_bpermute_b32 v112, v244, v184
	ds_bpermute_b32 v113, v244, v185
	ds_bpermute_b32 v114, v244, v186
	ds_bpermute_b32 v115, v244, v187
	ds_bpermute_b32 v92, v244, v192
	ds_bpermute_b32 v93, v244, v193
	ds_bpermute_b32 v94, v244, v194
	ds_bpermute_b32 v95, v244, v195
	ds_bpermute_b32 v88, v244, v210
	ds_bpermute_b32 v89, v244, v211
	ds_bpermute_b32 v90, v244, v212
	ds_bpermute_b32 v91, v244, v213
	ds_bpermute_b32 v84, v244, v214
	ds_bpermute_b32 v85, v244, v215
	ds_bpermute_b32 v86, v244, v216
	ds_bpermute_b32 v87, v244, v217
	ds_bpermute_b32 v80, v244, v218
	ds_bpermute_b32 v81, v244, v219
	ds_bpermute_b32 v82, v244, v220
	ds_bpermute_b32 v83, v244, v221
	ds_bpermute_b32 v72, v244, v222
	ds_bpermute_b32 v73, v244, v223
	ds_bpermute_b32 v74, v244, v224
	ds_bpermute_b32 v75, v244, v225
	ds_bpermute_b32 v76, v244, v234
	ds_bpermute_b32 v77, v244, v235
	ds_bpermute_b32 v78, v244, v236
	ds_bpermute_b32 v79, v244, v237
	ds_bpermute_b32 v68, v244, v248
	ds_bpermute_b32 v69, v244, v249
	ds_bpermute_b32 v70, v244, v250
	ds_bpermute_b32 v71, v244, v251
	s_waitcnt lgkmcnt(0)
	v_lshlrev_b32_e32 v97, 16, v112
	v_add_f32_e32 v64, v64, v97
	v_and_b32_e32 v97, 0xffff0000, v112
	v_add_f32_e32 v65, v65, v97
	v_lshlrev_b32_e32 v97, 16, v113
	v_add_f32_e32 v66, v66, v97
	v_and_b32_e32 v97, 0xffff0000, v113
	v_add_f32_e32 v67, v67, v97
	v_lshlrev_b32_e32 v97, 16, v114
	v_add_f32_e32 v97, v60, v97
	v_and_b32_e32 v60, 0xffff0000, v114
	v_add_f32_e32 v101, v61, v60
	v_lshlrev_b32_e32 v60, 16, v115
	v_add_f32_e32 v105, v62, v60
	v_and_b32_e32 v60, 0xffff0000, v115
	v_add_f32_e32 v109, v63, v60
	v_cvt_pk_bf16_f32 v60, v64, v65
	v_cvt_pk_bf16_f32 v61, v66, v67
	v_cvt_pk_bf16_f32 v62, v97, v101
	v_cvt_pk_bf16_f32 v63, v105, v109
	ds_bpermute_b32 v226, v242, v60
	ds_bpermute_b32 v227, v242, v61
	ds_bpermute_b32 v228, v242, v62
	ds_bpermute_b32 v229, v242, v63
	s_waitcnt lgkmcnt(4)
	global_store_dwordx4 v[174:175], v[230:233], off offset:256
	s_nop 1
	v_mul_f32_e32 v60, v65, v65
	v_mul_f32_e32 v61, v67, v67
	v_fmac_f32_e32 v60, v64, v64
	v_fmac_f32_e32 v61, v66, v66
	v_add_f32_e32 v60, v60, v61
	v_mul_f32_e32 v61, v101, v101
	v_mul_f32_e32 v62, v109, v109
	v_fmac_f32_e32 v61, v97, v97
	v_fmac_f32_e32 v62, v105, v105
	v_add_f32_e32 v61, v61, v62
	v_add_f32_e32 v60, v60, v61
	v_lshlrev_b32_e32 v61, 16, v92
	v_add_f32_e32 v56, v56, v61
	v_and_b32_e32 v61, 0xffff0000, v92
	v_add_f32_e32 v57, v57, v61
	v_lshlrev_b32_e32 v61, 16, v93
	v_add_f32_e32 v58, v58, v61
	v_and_b32_e32 v61, 0xffff0000, v93
	v_add_f32_e32 v59, v59, v61
	v_lshlrev_b32_e32 v61, 16, v94
	v_add_f32_e32 v61, v52, v61
	v_and_b32_e32 v52, 0xffff0000, v94
	v_add_f32_e32 v62, v53, v52
	v_lshlrev_b32_e32 v52, 16, v95
	v_add_f32_e32 v63, v54, v52
	v_and_b32_e32 v52, 0xffff0000, v95
	v_add_f32_e32 v64, v55, v52
	v_cvt_pk_bf16_f32 v52, v56, v57
	v_cvt_pk_bf16_f32 v53, v58, v59
	v_cvt_pk_bf16_f32 v54, v61, v62
	v_cvt_pk_bf16_f32 v55, v63, v64
	ds_bpermute_b32 v230, v242, v52
	ds_bpermute_b32 v231, v242, v53
	ds_bpermute_b32 v232, v242, v54
	ds_bpermute_b32 v233, v242, v55
	s_waitcnt lgkmcnt(4)
	global_store_dwordx4 v[110:111], v[226:229], off
	s_nop 1
	v_mul_f32_e32 v52, v57, v57
	v_mul_f32_e32 v53, v59, v59
	v_fmac_f32_e32 v52, v56, v56
	v_fmac_f32_e32 v53, v58, v58
	v_add_f32_e32 v52, v52, v53
	v_mul_f32_e32 v53, v62, v62
	v_mul_f32_e32 v54, v64, v64
	v_fmac_f32_e32 v53, v61, v61
	v_fmac_f32_e32 v54, v63, v63
	v_add_f32_e32 v53, v53, v54
	v_add_f32_e32 v52, v52, v53
	v_add_f32_e32 v52, v60, v52
	ds_bpermute_b32 v53, v204, v52
	s_waitcnt lgkmcnt(0)
	v_add_f32_e32 v52, v52, v53
	ds_bpermute_b32 v53, v203, v52
	s_and_saveexec_b64 s[38:39], vcc
	s_cbranch_execz .LBB0_952
	v_lshl_add_u32 v54, v108, 4, s35
	s_waitcnt lgkmcnt(0)
	v_add_f32_e32 v52, v52, v53
	ds_write_b32 v54, v52
.LBB0_952:
	s_or_b64 exec, exec, s[38:39]
	v_lshlrev_b32_e32 v52, 16, v88
	v_add_f32_e32 v48, v48, v52
	v_and_b32_e32 v52, 0xffff0000, v88
	v_add_f32_e32 v49, v49, v52
	v_lshlrev_b32_e32 v52, 16, v89
	v_add_f32_e32 v50, v50, v52
	v_and_b32_e32 v52, 0xffff0000, v89
	v_add_f32_e32 v51, v51, v52
	v_lshlrev_b32_e32 v52, 16, v90
	v_add_f32_e32 v52, v44, v52
	v_and_b32_e32 v44, 0xffff0000, v90
	s_waitcnt lgkmcnt(0)
	v_add_f32_e32 v53, v45, v44
	v_lshlrev_b32_e32 v44, 16, v91
	v_add_f32_e32 v54, v46, v44
	v_and_b32_e32 v44, 0xffff0000, v91
	v_mul_f32_e32 v46, v49, v49
	v_add_f32_e32 v47, v47, v44
	v_cvt_pk_bf16_f32 v44, v48, v49
	v_fmac_f32_e32 v46, v48, v48
	v_mul_f32_e32 v48, v51, v51
	v_fmac_f32_e32 v48, v50, v50
	v_add_f32_e32 v46, v46, v48
	v_mul_f32_e32 v48, v53, v53
	v_mul_f32_e32 v49, v47, v47
	v_fmac_f32_e32 v48, v52, v52
	v_fmac_f32_e32 v49, v54, v54
	v_add_f32_e32 v48, v48, v49
	v_add_f32_e32 v46, v46, v48
	v_lshlrev_b32_e32 v48, 16, v84
	v_add_f32_e32 v40, v40, v48
	v_and_b32_e32 v48, 0xffff0000, v84
	v_add_f32_e32 v41, v41, v48
	v_lshlrev_b32_e32 v48, 16, v85
	v_add_f32_e32 v42, v42, v48
	v_and_b32_e32 v48, 0xffff0000, v85
	v_add_f32_e32 v43, v43, v48
	v_lshlrev_b32_e32 v48, 16, v86
	v_add_f32_e32 v48, v36, v48
	v_and_b32_e32 v36, 0xffff0000, v86
	v_add_f32_e32 v49, v37, v36
	v_lshlrev_b32_e32 v36, 16, v87
	v_cvt_pk_bf16_f32 v45, v50, v51
	v_add_f32_e32 v50, v38, v36
	v_and_b32_e32 v36, 0xffff0000, v87
	v_add_f32_e32 v51, v39, v36
	v_mul_f32_e32 v36, v41, v41
	v_mul_f32_e32 v37, v43, v43
	v_fmac_f32_e32 v36, v40, v40
	v_fmac_f32_e32 v37, v42, v42
	v_add_f32_e32 v36, v36, v37
	v_mul_f32_e32 v37, v49, v49
	v_mul_f32_e32 v38, v51, v51
	v_fmac_f32_e32 v37, v48, v48
	v_fmac_f32_e32 v38, v50, v50
	v_add_f32_e32 v37, v37, v38
	v_add_f32_e32 v36, v36, v37
	v_add_f32_e32 v36, v46, v36
	ds_bpermute_b32 v37, v204, v36
	v_cvt_pk_bf16_f32 v46, v52, v53
	v_cvt_pk_bf16_f32 v47, v54, v47
	ds_bpermute_b32 v226, v242, v44
	ds_bpermute_b32 v227, v242, v45
	ds_bpermute_b32 v228, v242, v46
	ds_bpermute_b32 v229, v242, v47
	s_waitcnt lgkmcnt(4)
	global_store_dwordx4 v[110:111], v[230:233], off offset:256
	v_cvt_pk_bf16_f32 v38, v40, v41
	s_waitcnt lgkmcnt(0)
	v_add_f32_e32 v36, v36, v37
	ds_bpermute_b32 v37, v203, v36
	v_cvt_pk_bf16_f32 v39, v42, v43
	v_cvt_pk_bf16_f32 v40, v48, v49
	v_cvt_pk_bf16_f32 v41, v50, v51
	ds_bpermute_b32 v230, v242, v38
	ds_bpermute_b32 v231, v242, v39
	ds_bpermute_b32 v232, v242, v40
	ds_bpermute_b32 v233, v242, v41
	s_waitcnt lgkmcnt(4)
	global_store_dwordx4 v[106:107], v[226:229], off
	s_and_saveexec_b64 s[38:39], vcc
	s_cbranch_execz .LBB0_954
	v_lshl_add_u32 v38, v104, 4, s35
	s_waitcnt lgkmcnt(0)
	v_add_f32_e32 v36, v36, v37
	ds_write_b32 v38, v36
.LBB0_954:
	s_or_b64 exec, exec, s[38:39]
	v_lshlrev_b32_e32 v36, 16, v80
	v_add_f32_e32 v32, v32, v36
	v_and_b32_e32 v36, 0xffff0000, v80
	v_add_f32_e32 v33, v33, v36
	v_lshlrev_b32_e32 v36, 16, v81
	v_add_f32_e32 v34, v34, v36
	v_and_b32_e32 v36, 0xffff0000, v81
	v_add_f32_e32 v35, v35, v36
	v_lshlrev_b32_e32 v36, 16, v82
	v_add_f32_e32 v36, v28, v36
	v_and_b32_e32 v28, 0xffff0000, v82
	s_waitcnt lgkmcnt(0)
	v_add_f32_e32 v37, v29, v28
	v_lshlrev_b32_e32 v28, 16, v83
	v_add_f32_e32 v38, v30, v28
	v_and_b32_e32 v28, 0xffff0000, v83
	v_mul_f32_e32 v30, v33, v33
	v_add_f32_e32 v31, v31, v28
	v_cvt_pk_bf16_f32 v28, v32, v33
	v_fmac_f32_e32 v30, v32, v32
	v_mul_f32_e32 v32, v35, v35
	v_fmac_f32_e32 v32, v34, v34
	v_add_f32_e32 v30, v30, v32
	v_mul_f32_e32 v32, v37, v37
	v_mul_f32_e32 v33, v31, v31
	v_fmac_f32_e32 v32, v36, v36
	v_fmac_f32_e32 v33, v38, v38
	v_add_f32_e32 v32, v32, v33
	v_add_f32_e32 v30, v30, v32
	v_lshlrev_b32_e32 v32, 16, v72
	v_add_f32_e32 v24, v24, v32
	v_and_b32_e32 v32, 0xffff0000, v72
	v_add_f32_e32 v25, v25, v32
	v_lshlrev_b32_e32 v32, 16, v73
	v_add_f32_e32 v26, v26, v32
	v_and_b32_e32 v32, 0xffff0000, v73
	v_add_f32_e32 v27, v27, v32
	v_lshlrev_b32_e32 v32, 16, v74
	v_add_f32_e32 v32, v20, v32
	v_and_b32_e32 v20, 0xffff0000, v74
	v_add_f32_e32 v33, v21, v20
	v_lshlrev_b32_e32 v20, 16, v75
	v_cvt_pk_bf16_f32 v29, v34, v35
	v_add_f32_e32 v34, v22, v20
	v_and_b32_e32 v20, 0xffff0000, v75
	v_add_f32_e32 v35, v23, v20
	v_mul_f32_e32 v20, v25, v25
	v_mul_f32_e32 v21, v27, v27
	v_fmac_f32_e32 v20, v24, v24
	v_fmac_f32_e32 v21, v26, v26
	v_add_f32_e32 v20, v20, v21
	v_mul_f32_e32 v21, v33, v33
	v_mul_f32_e32 v22, v35, v35
	v_fmac_f32_e32 v21, v32, v32
	v_fmac_f32_e32 v22, v34, v34
	v_add_f32_e32 v21, v21, v22
	v_add_f32_e32 v20, v20, v21
	v_add_f32_e32 v20, v30, v20
	ds_bpermute_b32 v21, v204, v20
	v_cvt_pk_bf16_f32 v30, v36, v37
	v_cvt_pk_bf16_f32 v31, v38, v31
	ds_bpermute_b32 v226, v242, v28
	ds_bpermute_b32 v227, v242, v29
	ds_bpermute_b32 v228, v242, v30
	ds_bpermute_b32 v229, v242, v31
	s_waitcnt lgkmcnt(4)
	global_store_dwordx4 v[106:107], v[230:233], off offset:256
	v_cvt_pk_bf16_f32 v22, v24, v25
	s_waitcnt lgkmcnt(0)
	v_add_f32_e32 v20, v20, v21
	ds_bpermute_b32 v21, v203, v20
	v_cvt_pk_bf16_f32 v23, v26, v27
	v_cvt_pk_bf16_f32 v24, v32, v33
	v_cvt_pk_bf16_f32 v25, v34, v35
	ds_bpermute_b32 v230, v242, v22
	ds_bpermute_b32 v231, v242, v23
	ds_bpermute_b32 v232, v242, v24
	ds_bpermute_b32 v233, v242, v25
	s_waitcnt lgkmcnt(4)
	global_store_dwordx4 v[102:103], v[226:229], off
	s_and_saveexec_b64 s[38:39], vcc
	s_cbranch_execz .LBB0_956
	v_lshl_add_u32 v22, v100, 4, s35
	s_waitcnt lgkmcnt(0)
	v_add_f32_e32 v20, v20, v21
	ds_write_b32 v22, v20
.LBB0_956:
	s_or_b64 exec, exec, s[38:39]
	v_lshlrev_b32_e32 v20, 16, v76
	v_add_f32_e32 v16, v16, v20
	v_and_b32_e32 v20, 0xffff0000, v76
	v_add_f32_e32 v17, v17, v20
	v_lshlrev_b32_e32 v20, 16, v77
	v_add_f32_e32 v18, v18, v20
	v_and_b32_e32 v20, 0xffff0000, v77
	v_add_f32_e32 v19, v19, v20
	v_lshlrev_b32_e32 v20, 16, v78
	v_add_f32_e32 v20, v12, v20
	v_and_b32_e32 v12, 0xffff0000, v78
	s_waitcnt lgkmcnt(0)
	v_add_f32_e32 v21, v13, v12
	v_lshlrev_b32_e32 v12, 16, v79
	v_add_f32_e32 v22, v14, v12
	v_and_b32_e32 v12, 0xffff0000, v79
	v_mul_f32_e32 v14, v17, v17
	v_add_f32_e32 v15, v15, v12
	v_cvt_pk_bf16_f32 v12, v16, v17
	v_fmac_f32_e32 v14, v16, v16
	v_mul_f32_e32 v16, v19, v19
	v_fmac_f32_e32 v16, v18, v18
	v_add_f32_e32 v14, v14, v16
	v_mul_f32_e32 v16, v21, v21
	v_mul_f32_e32 v17, v15, v15
	v_fmac_f32_e32 v16, v20, v20
	v_fmac_f32_e32 v17, v22, v22
	v_add_f32_e32 v16, v16, v17
	v_add_f32_e32 v14, v14, v16
	v_lshlrev_b32_e32 v16, 16, v68
	v_add_f32_e32 v8, v8, v16
	v_and_b32_e32 v16, 0xffff0000, v68
	v_add_f32_e32 v9, v9, v16
	v_lshlrev_b32_e32 v16, 16, v69
	v_add_f32_e32 v10, v10, v16
	v_and_b32_e32 v16, 0xffff0000, v69
	v_add_f32_e32 v11, v11, v16
	v_lshlrev_b32_e32 v16, 16, v70
	v_add_f32_e32 v16, v4, v16
	v_and_b32_e32 v4, 0xffff0000, v70
	v_add_f32_e32 v17, v5, v4
	v_lshlrev_b32_e32 v4, 16, v71
	v_cvt_pk_bf16_f32 v13, v18, v19
	v_add_f32_e32 v18, v6, v4
	v_and_b32_e32 v4, 0xffff0000, v71
	v_add_f32_e32 v19, v7, v4
	v_mul_f32_e32 v4, v9, v9
	v_mul_f32_e32 v5, v11, v11
	v_fmac_f32_e32 v4, v8, v8
	v_fmac_f32_e32 v5, v10, v10
	v_add_f32_e32 v4, v4, v5
	v_mul_f32_e32 v5, v17, v17
	v_mul_f32_e32 v6, v19, v19
	v_fmac_f32_e32 v5, v16, v16
	v_fmac_f32_e32 v6, v18, v18
	v_add_f32_e32 v5, v5, v6
	v_add_f32_e32 v4, v4, v5
	v_add_f32_e32 v4, v14, v4
	ds_bpermute_b32 v5, v204, v4
	v_cvt_pk_bf16_f32 v14, v20, v21
	v_cvt_pk_bf16_f32 v15, v22, v15
	ds_bpermute_b32 v226, v242, v12
	ds_bpermute_b32 v227, v242, v13
	ds_bpermute_b32 v228, v242, v14
	ds_bpermute_b32 v229, v242, v15
	s_waitcnt lgkmcnt(4)
	global_store_dwordx4 v[102:103], v[230:233], off offset:256
	v_cvt_pk_bf16_f32 v6, v8, v9
	s_waitcnt lgkmcnt(0)
	v_add_f32_e32 v4, v4, v5
	ds_bpermute_b32 v5, v203, v4
	v_cvt_pk_bf16_f32 v7, v10, v11
	v_cvt_pk_bf16_f32 v8, v16, v17
	v_cvt_pk_bf16_f32 v9, v18, v19
	ds_bpermute_b32 v230, v242, v6
	ds_bpermute_b32 v231, v242, v7
	ds_bpermute_b32 v232, v242, v8
	ds_bpermute_b32 v233, v242, v9
	s_waitcnt lgkmcnt(4)
	global_store_dwordx4 v[98:99], v[226:229], off
	s_and_saveexec_b64 s[38:39], vcc
	s_cbranch_execz .LBB0_958
	v_lshl_add_u32 v6, v96, 4, s35
	s_waitcnt lgkmcnt(0)
	v_add_f32_e32 v4, v4, v5
	ds_write_b32 v6, v4
.LBB0_958:
	s_or_b64 exec, exec, s[38:39]
	s_lshl_b32 s31, s31, 8
	s_lshl_b32 s35, s40, 6
	s_waitcnt lgkmcnt(0)
	global_store_dwordx4 v[98:99], v[230:233], off offset:256
	s_barrier
	s_add_i32 s31, s31, s35
	v_add_u32_e32 v4, s31, v202
	v_cmp_gt_i32_e32 vcc, s82, v4
	s_and_saveexec_b64 s[38:39], vcc
	s_cbranch_execz .LBB0_960
	s_waitcnt lgkmcnt(0)
	v_lshl_add_u32 v5, v4, 4, 0
	v_add_u32_e32 v5, 0x20000, v5
	ds_read_b128 v[6:9], v5
	v_lshl_add_u32 v4, s34, 8, v4
	v_ashrrev_i32_e32 v5, 31, v4
	s_ashr_i32 s31, s30, 31
	v_lshl_add_u64 v[4:5], v[4:5], 4, s[0:1]
	s_waitcnt lgkmcnt(0)
	v_mov_b32_e32 v10, v7
	v_mov_b32_e32 v11, v8
	v_mov_b32_e32 v7, v9
	v_pk_add_f32 v[6:7], v[10:11], v[6:7]
	v_lshl_add_u64 v[4:5], s[30:31], 2, v[4:5]
	v_add_f32_e32 v6, v6, v7
	global_store_dword v[4:5], v6, off

.LBB0_969:
	s_add_i32 s49, s24, 0x10000
	s_and_b32 s49, s49, 0x18000
	s_add_i32 s49, s57, s49
	s_waitcnt vmcnt(4)
	s_barrier
	s_add_i32 s52, s49, 0x2000
	v_lshl_add_u64 v[40:41], s[8:9], 0, v[22:23]
	s_mov_b32 m0, s49
	s_add_i32 s51, s49, 0x4000
	v_lshl_add_u64 v[38:39], s[10:11], 0, v[22:23]
	global_load_lds_dwordx4 v[40:41], off
	s_mov_b32 m0, s52
	s_add_i32 s50, s49, 0x6000
	v_lshl_add_u64 v[36:37], s[16:17], 0, v[22:23]
	global_load_lds_dwordx4 v[38:39], off
	s_mov_b32 m0, s51
	v_lshl_add_u64 v[34:35], s[18:19], 0, v[22:23]
	global_load_lds_dwordx4 v[36:37], off
	s_mov_b32 m0, s50
	s_and_b32 s49, s24, 0x18000
	global_load_lds_dwordx4 v[34:35], off
	s_add_i32 s49, s33, s49
	v_add_u32_e32 v2, s49, v30
	v_add_u32_e32 v33, s84, v2
	ds_read_b128 v[34:37], v33
	ds_read_b128 v[38:41], v2 offset:8192
	ds_read_b128 v[50:53], v2 offset:10240
	ds_read_b128 v[54:57], v2 offset:12288
	ds_read_b128 v[58:61], v2 offset:14336
	ds_read_b128 v[46:49], v33 offset:1024
	ds_read_b128 v[62:65], v2 offset:9216
	ds_read_b128 v[66:69], v2 offset:11264
	ds_read_b128 v[70:73], v2 offset:13312
	ds_read_b128 v[74:77], v2 offset:15360
	s_add_i32 s48, s48, 1
	s_add_i32 s24, s24, 0x8000
	s_add_u32 s8, s8, 0x80
	s_addc_u32 s9, s9, 0
	s_add_u32 s10, s10, 0x80
	s_addc_u32 s11, s11, 0
	s_add_u32 s16, s16, 0x80
	s_addc_u32 s17, s17, 0
	s_add_u32 s18, s18, 0x80
	s_addc_u32 s19, s19, 0
	s_waitcnt lgkmcnt(8)
	v_mfma_f32_16x16x32_bf16 v[4:7], v[38:41], v[34:37], v[4:7]
	s_waitcnt lgkmcnt(7)
	v_mfma_f32_16x16x32_bf16 v[8:11], v[50:53], v[34:37], v[8:11]
	s_waitcnt lgkmcnt(6)
	v_mfma_f32_16x16x32_bf16 v[12:15], v[54:57], v[34:37], v[12:15]
	s_waitcnt lgkmcnt(5)
	v_mfma_f32_16x16x32_bf16 v[16:19], v[58:61], v[34:37], v[16:19]
	s_waitcnt lgkmcnt(3)
	v_mfma_f32_16x16x32_bf16 v[4:7], v[62:65], v[46:49], v[4:7]
	s_waitcnt lgkmcnt(2)
	v_mfma_f32_16x16x32_bf16 v[8:11], v[66:69], v[46:49], v[8:11]
	s_waitcnt lgkmcnt(1)
	v_mfma_f32_16x16x32_bf16 v[12:15], v[70:73], v[46:49], v[12:15]
	s_cmp_eq_u32 s27, s48
	s_waitcnt lgkmcnt(0)
	v_mfma_f32_16x16x32_bf16 v[16:19], v[74:77], v[46:49], v[16:19]
	s_cbranch_scc0 .LBB0_969
	s_lshl_b32 s8, s27, 15
	s_and_b32 s8, s8, 0x18000
	s_add_i32 s8, s33, s8
	v_add_u32_e32 v2, s8, v30
	s_waitcnt vmcnt(4)
	s_barrier
	v_add_u32_e32 v33, s84, v2
	ds_read_b128 v[34:37], v33
	ds_read_b128 v[38:41], v2 offset:8192
	ds_read_b128 v[50:53], v2 offset:10240
	ds_read_b128 v[54:57], v2 offset:12288
	ds_read_b128 v[58:61], v2 offset:14336
	ds_read_b128 v[46:49], v33 offset:1024
	ds_read_b128 v[62:65], v2 offset:9216
	ds_read_b128 v[66:69], v2 offset:11264
	ds_read_b128 v[70:73], v2 offset:13312
	ds_read_b128 v[74:77], v2 offset:15360
	v_readlane_b32 s8, v254, 13
	v_readlane_b32 s9, v254, 14
	s_waitcnt lgkmcnt(8)
	v_mfma_f32_16x16x32_bf16 v[4:7], v[38:41], v[34:37], v[4:7]
	s_waitcnt lgkmcnt(7)
	v_mfma_f32_16x16x32_bf16 v[8:11], v[50:53], v[34:37], v[8:11]
	s_waitcnt lgkmcnt(6)
	v_mfma_f32_16x16x32_bf16 v[12:15], v[54:57], v[34:37], v[12:15]
	s_waitcnt lgkmcnt(5)
	v_mfma_f32_16x16x32_bf16 v[16:19], v[58:61], v[34:37], v[16:19]
	s_waitcnt lgkmcnt(3)
	v_mfma_f32_16x16x32_bf16 v[4:7], v[62:65], v[46:49], v[4:7]
	s_waitcnt lgkmcnt(2)
	v_mfma_f32_16x16x32_bf16 v[8:11], v[66:69], v[46:49], v[8:11]
	s_waitcnt lgkmcnt(1)
	v_mfma_f32_16x16x32_bf16 v[12:15], v[70:73], v[46:49], v[12:15]
	s_waitcnt lgkmcnt(0)
	v_mfma_f32_16x16x32_bf16 v[16:19], v[74:77], v[46:49], v[16:19]
	s_and_b64 vcc, exec, s[8:9]
	s_waitcnt vmcnt(0)
	s_barrier
	v_add_u32_e32 v2, s33, v31
	ds_read_b128 v[34:37], v32
	ds_read_b128 v[38:41], v2 offset:8192
	ds_read_b128 v[50:53], v2 offset:10240
	ds_read_b128 v[54:57], v2 offset:12288
	ds_read_b128 v[58:61], v2 offset:14336
	ds_read_b128 v[46:49], v32 offset:1024
	ds_read_b128 v[62:65], v2 offset:9216
	ds_read_b128 v[66:69], v2 offset:11264
	ds_read_b128 v[70:73], v2 offset:13312
	ds_read_b128 v[74:77], v2 offset:15360
	s_waitcnt lgkmcnt(8)
	v_mfma_f32_16x16x32_bf16 v[4:7], v[38:41], v[34:37], v[4:7]
	s_waitcnt lgkmcnt(7)
	v_mfma_f32_16x16x32_bf16 v[8:11], v[50:53], v[34:37], v[8:11]
	s_waitcnt lgkmcnt(6)
	v_mfma_f32_16x16x32_bf16 v[12:15], v[54:57], v[34:37], v[12:15]
	s_waitcnt lgkmcnt(5)
	v_mfma_f32_16x16x32_bf16 v[16:19], v[58:61], v[34:37], v[16:19]
	s_waitcnt lgkmcnt(3)
	v_mfma_f32_16x16x32_bf16 v[4:7], v[62:65], v[46:49], v[4:7]
	s_waitcnt lgkmcnt(2)
	v_mfma_f32_16x16x32_bf16 v[8:11], v[66:69], v[46:49], v[8:11]
	s_waitcnt lgkmcnt(1)
	v_mfma_f32_16x16x32_bf16 v[12:15], v[70:73], v[46:49], v[12:15]
	s_waitcnt lgkmcnt(0)
	v_mfma_f32_16x16x32_bf16 v[16:19], v[74:77], v[46:49], v[16:19]
	s_nop 1
	s_barrier
	s_cbranch_vccz .LBB0_974
	v_add_u32_e32 v2, s85, v24
	ds_write_b128 v2, v[4:7]
	ds_write_b128 v2, v[8:11] offset:1024
	ds_write_b128 v2, v[12:15] offset:2048
	s_nop 2
	ds_write_b128 v2, v[16:19] offset:3072
	s_and_saveexec_b64 s[8:9], s[4:5]
	ds_write_b32 v28, v3 offset:16384
	s_or_b64 exec, exec, s[8:9]
